# D1+A2 plus A1: softmax-wave QK^T K-fragment prefetch (16 ds_read_b128 in flight, counted lgkmcnt)
# baseline (speedup 1.0000x reference)
; #define SBAR() __builtin_amdgcn_sched_barrier(0)
; #define A2_LOADT(t) do { const size_t ro_ = (size_t)((t) * 64 + sr) * D + sc; \
;         sk0 = att::load8(c.K + ro_); sk1 = att::load8(c.K + ro_ + 32 * D); sv00 = att::load8(c.V0 + ro_); sv01 = att::load8(c.V0 + ro_ + 32 * D); sv10 = att::load8(c.V1 + ro_); sv11 = att::load8(c.V1 + ro_ + 32 * D); } while (0)
; __device__ __forceinline__ void qkt_rt(f32x16& p0, f32x16& p1, const char* Kb, int r32, int hi, const bf16x8* qr) {
;     p0 = f32x16{}; p1 = f32x16{};
;     const char* kb[4];
; #pragma unroll
;     for (int dd = 0; dd < 4; ++dd) kb[dd] = Kb + KSWZ(r32, (dd * 16 + hi * 8) * 2);
; #pragma unroll
;     for (int d0 = 0; d0 < 8; ++d0) { const char* a = kb[d0 & 3] + (d0 >> 2) * 128;
;         bf16x8 b0 = *reinterpret_cast<const bf16x8*>(a);
;         bf16x8 b1 = *reinterpret_cast<const bf16x8*>(a + 32 * 256);
;         p0 = __builtin_amdgcn_mfma_f32_32x32x16_bf16(b0, qr[d0], p0, 0, 0, 0);
;         p1 = __builtin_amdgcn_mfma_f32_32x32x16_bf16(b1, qr[d0], p1, 0, 0, 0); }
; }
; __device__ __forceinline__ void attn2_block(const Blk& c, char* lds) {
;     ...
;         for (int s = 0; s <= NT; ++s) {
;             const int par = s & 1;
;             if (s + 1 < NT) A2_LOADT(s + 1);
;             SBAR();
;             if (s < NT) {
;                 f32x16 p0, p1; float mn, al; bf16x8 pa0, pa1, pa2, pa3;
;                 qkt_rt(p0, p1, lds + L_K + par * SHM_K, r32, hi, qr);
;                 const int kb_ = s * 64;
.LBB0_552:
	s_and_b32 s88, s30, 1
	s_lshl_b32 s10, s88, 15
	s_add_i32 s10, s10, s100
	s_mov_b32 m0, s10
	v_lshl_add_u64 v[52:53], v[168:169], 0, s[82:83]
	global_load_lds_dwordx4 v[52:53], off
	s_add_i32 m0, s10, 0x380
	v_lshl_add_u64 v[54:55], v[170:171], 0, s[82:83]
	global_load_lds_dwordx4 v[52:53], off offset:128
	s_add_i32 m0, s10, 0x4000
	s_nop 0
	global_load_lds_dwordx4 v[54:55], off
	s_add_i32 m0, s10, 0x4380
	s_nop 0
	global_load_lds_dwordx4 v[54:55], off offset:128
	s_xor_b32 s10, s88, 1
	s_lshl_b32 s10, s10, 14
	s_add_i32 s10, s10, s100
	s_add_i32 m0, s10, 0x10000
	v_lshl_add_u64 v[56:57], v[164:165], 0, s[82:83]
	v_lshl_add_u64 v[58:59], v[166:167], 0, s[82:83]
	global_load_lds_dwordx4 v[56:57], off
	global_load_lds_dwordx4 v[58:59], off offset:1024
	s_lshl_b32 s10, s88, 14
	s_add_i32 s10, s10, 0
	s_add_i32 s10, s10, 0x10000
	v_add3_u32 v250, s10, v121, v119
	v_add3_u32 v251, s10, v122, v119
	v_add3_u32 v252, s10, v123, v119
	v_add3_u32 v253, s10, v124, v119
	s_add_i32 s10, s84, 63
	s_cmp_le_i32 s10, s86
	ds_read_b128 v[132:135], v250
	ds_read_b128 v[136:139], v250 offset:8192
	ds_read_b128 v[140:143], v251
	ds_read_b128 v[144:147], v251 offset:8192
	ds_read_b128 v[148:151], v252
	ds_read_b128 v[152:155], v252 offset:8192
	ds_read_b128 v[52:55], v253
	ds_read_b128 v[56:59], v253 offset:8192
	ds_read_b128 v[60:63], v250 offset:128
	ds_read_b128 v[64:67], v250 offset:8320
	ds_read_b128 v[68:71], v251 offset:128
	ds_read_b128 v[72:75], v251 offset:8320
	ds_read_b128 v[36:39], v252 offset:128
	ds_read_b128 v[40:43], v252 offset:8320
	s_waitcnt lgkmcnt(13)
	v_mfma_f32_32x32x16_bf16 v[20:35], v[132:135], v[104:107], 0
	ds_read_b128 v[44:47], v253 offset:128
	s_waitcnt lgkmcnt(13)
	v_mfma_f32_32x32x16_bf16 v[4:19], v[136:139], v[104:107], 0
	ds_read_b128 v[48:51], v253 offset:8320
	s_waitcnt lgkmcnt(13)
	v_mfma_f32_32x32x16_bf16 v[20:35], v[140:143], v[100:103], v[20:35]
	s_waitcnt lgkmcnt(12)
	v_mfma_f32_32x32x16_bf16 v[4:19], v[144:147], v[100:103], v[4:19]
	s_waitcnt lgkmcnt(11)
	v_mfma_f32_32x32x16_bf16 v[20:35], v[148:151], v[96:99], v[20:35]
	s_waitcnt lgkmcnt(10)
	v_mfma_f32_32x32x16_bf16 v[4:19], v[152:155], v[96:99], v[4:19]
	s_waitcnt lgkmcnt(9)
	v_mfma_f32_32x32x16_bf16 v[20:35], v[52:55], v[92:95], v[20:35]
	s_waitcnt lgkmcnt(8)
	v_mfma_f32_32x32x16_bf16 v[4:19], v[56:59], v[92:95], v[4:19]
	s_waitcnt lgkmcnt(7)
	v_mfma_f32_32x32x16_bf16 v[20:35], v[60:63], v[88:91], v[20:35]
	s_waitcnt lgkmcnt(6)
	v_mfma_f32_32x32x16_bf16 v[4:19], v[64:67], v[88:91], v[4:19]
	s_waitcnt lgkmcnt(5)
	v_mfma_f32_32x32x16_bf16 v[20:35], v[68:71], v[84:87], v[20:35]
	s_waitcnt lgkmcnt(4)
	v_mfma_f32_32x32x16_bf16 v[4:19], v[72:75], v[84:87], v[4:19]
	s_waitcnt lgkmcnt(3)
	v_mfma_f32_32x32x16_bf16 v[20:35], v[36:39], v[80:83], v[20:35]
	s_waitcnt lgkmcnt(2)
	v_mfma_f32_32x32x16_bf16 v[4:19], v[40:43], v[80:83], v[4:19]
	s_waitcnt lgkmcnt(1)
	v_mfma_f32_32x32x16_bf16 v[20:35], v[44:47], v[76:79], v[20:35]
	s_waitcnt lgkmcnt(0)
	v_mfma_f32_32x32x16_bf16 v[4:19], v[48:51], v[76:79], v[4:19]
	s_cbranch_scc1 .LBB0_586
; __device__ __forceinline__ void bias_mask_tile(f32x16& p0, f32x16& p1, int dq, const float* bt) {
;     const float NEG = -__builtin_inff();
; #pragma unroll
;     for (int r = 0; r < 16; ++r) {
;         const int c = (r & 3) + 8 * (r >> 2);
;         const int d0 = dq - c, d1 = dq - c - 32;
;         const unsigned i0 = (unsigned)d0 < 255u ? (unsigned)d0 : 255u, i1 = (unsigned)d1 < 255u ? (unsigned)d1 : 255u;
;         const float b0 = bt[i0], b1 = bt[i1];
;         p0[r] = d0 >= 0 ? p0[r] + b0 : NEG;
;         p1[r] = d1 >= 0 ? p1[r] + b1 : NEG;
;     }
; }
	v_add_u32_e32 v115, 27, v125
	v_lshl_add_u32 v36, v115, 2, s64
	v_add_u32_e32 v36, 0xffffff14, v36
	ds_read_b32 v132, v36 offset:236
	ds_read_b32 v133, v36 offset:232
	ds_read_b32 v134, v36 offset:228
	ds_read_b32 v135, v36 offset:224
	ds_read_b32 v136, v36 offset:204
	ds_read_b32 v137, v36 offset:200
	ds_read_b32 v138, v36 offset:196
	ds_read_b32 v139, v36 offset:192
	ds_read_b32 v140, v36 offset:172
	ds_read_b32 v141, v36 offset:168
	ds_read_b32 v142, v36 offset:164
	ds_read_b32 v143, v36 offset:160
	ds_read_b32 v144, v36 offset:140
	ds_read_b32 v145, v36 offset:136
	ds_read_b32 v146, v36 offset:132
	v_cmp_lt_i32_e32 vcc, -1, v115
	v_cmp_lt_i32_e64 s[16:17], 0, v115
	s_waitcnt lgkmcnt(14)
	v_add_f32_e32 v20, v20, v132
	ds_read_b32 v147, v36 offset:128
	s_waitcnt lgkmcnt(14)
	v_add_f32_e32 v21, v21, v133
	ds_read_b32 v148, v36 offset:108
	v_cndmask_b32_e32 v20, v240, v20, vcc
	v_cndmask_b32_e64 v21, v240, v21, s[16:17]
	v_cmp_lt_i32_e32 vcc, 1, v115
	v_cmp_lt_i32_e64 s[16:17], 2, v115
	s_waitcnt lgkmcnt(14)
	v_add_f32_e32 v22, v22, v134
	ds_read_b32 v149, v36 offset:104
	s_waitcnt lgkmcnt(14)
	v_add_f32_e32 v23, v23, v135
	ds_read_b32 v150, v36 offset:100
	v_cndmask_b32_e32 v22, v240, v22, vcc
	v_cndmask_b32_e64 v23, v240, v23, s[16:17]
	v_cmp_lt_i32_e32 vcc, 7, v115
	v_cmp_lt_i32_e64 s[16:17], 8, v115
	s_waitcnt lgkmcnt(14)
	v_add_f32_e32 v24, v24, v136
	ds_read_b32 v151, v36 offset:96
	s_waitcnt lgkmcnt(14)
	v_add_f32_e32 v25, v25, v137
	ds_read_b32 v152, v36 offset:76
	v_cndmask_b32_e32 v24, v240, v24, vcc
	v_cndmask_b32_e64 v25, v240, v25, s[16:17]
	v_cmp_lt_i32_e32 vcc, 9, v115
	v_cmp_lt_i32_e64 s[16:17], 10, v115
	s_waitcnt lgkmcnt(14)
	v_add_f32_e32 v26, v26, v138
	ds_read_b32 v153, v36 offset:72
	s_waitcnt lgkmcnt(14)
	v_add_f32_e32 v27, v27, v139
	ds_read_b32 v154, v36 offset:68
	v_cndmask_b32_e32 v26, v240, v26, vcc
	v_cndmask_b32_e64 v27, v240, v27, s[16:17]
	v_cmp_lt_i32_e32 vcc, 15, v115
	v_cmp_lt_i32_e64 s[16:17], 16, v115
	s_waitcnt lgkmcnt(14)
	v_add_f32_e32 v28, v28, v140
	ds_read_b32 v155, v36 offset:64
	s_waitcnt lgkmcnt(14)
	v_add_f32_e32 v29, v29, v141
	ds_read_b32 v60, v36 offset:44
	v_cndmask_b32_e32 v28, v240, v28, vcc
	v_cndmask_b32_e64 v29, v240, v29, s[16:17]
	v_cmp_lt_i32_e32 vcc, 17, v115
	v_cmp_lt_i32_e64 s[16:17], 18, v115
	s_waitcnt lgkmcnt(14)
	v_add_f32_e32 v30, v30, v142
	ds_read_b32 v61, v36 offset:40
	s_waitcnt lgkmcnt(14)
	v_add_f32_e32 v31, v31, v143
	ds_read_b32 v62, v36 offset:36
	v_cndmask_b32_e32 v30, v240, v30, vcc
	v_cndmask_b32_e64 v31, v240, v31, s[16:17]
	v_cmp_lt_i32_e32 vcc, 23, v115
	v_cmp_lt_i32_e64 s[16:17], 24, v115
	s_waitcnt lgkmcnt(14)
	v_add_f32_e32 v32, v32, v144
	ds_read_b32 v63, v36 offset:32
	s_waitcnt lgkmcnt(14)
	v_add_f32_e32 v33, v33, v145
	ds_read_b32 v64, v36 offset:12
	v_cndmask_b32_e32 v32, v240, v32, vcc
	v_cndmask_b32_e64 v33, v240, v33, s[16:17]
	v_cmp_lt_i32_e32 vcc, 25, v115
	v_cmp_lt_i32_e64 s[16:17], 26, v115
	s_waitcnt lgkmcnt(14)
	v_add_f32_e32 v34, v34, v146
	ds_read_b32 v65, v36 offset:8
	s_waitcnt lgkmcnt(14)
	v_add_f32_e32 v35, v35, v147
	ds_read_b32 v66, v36 offset:4
	v_cndmask_b32_e32 v34, v240, v34, vcc
	v_cndmask_b32_e64 v35, v240, v35, s[16:17]
	v_cmp_lt_i32_e32 vcc, 31, v115
	v_cmp_lt_i32_e64 s[16:17], 32, v115
	s_waitcnt lgkmcnt(14)
	v_add_f32_e32 v4, v4, v148
	ds_read_b32 v67, v36 offset:0
	s_waitcnt lgkmcnt(14)
	v_add_f32_e32 v5, v5, v149
	v_cndmask_b32_e32 v4, v240, v4, vcc
	v_cndmask_b32_e64 v5, v240, v5, s[16:17]
	v_cmp_lt_i32_e32 vcc, 33, v115
	v_cmp_lt_i32_e64 s[16:17], 34, v115
	s_waitcnt lgkmcnt(13)
	v_add_f32_e32 v6, v6, v150
	s_waitcnt lgkmcnt(12)
	v_add_f32_e32 v7, v7, v151
	v_cndmask_b32_e32 v6, v240, v6, vcc
	v_cndmask_b32_e64 v7, v240, v7, s[16:17]
	v_cmp_lt_i32_e32 vcc, 39, v115
	v_cmp_lt_i32_e64 s[16:17], 40, v115
	s_waitcnt lgkmcnt(11)
	v_add_f32_e32 v8, v8, v152
	s_waitcnt lgkmcnt(10)
	v_add_f32_e32 v9, v9, v153
	v_cndmask_b32_e32 v8, v240, v8, vcc
	v_cndmask_b32_e64 v9, v240, v9, s[16:17]
	v_cmp_lt_i32_e32 vcc, 41, v115
	v_cmp_lt_i32_e64 s[16:17], 42, v115
	s_waitcnt lgkmcnt(9)
	v_add_f32_e32 v10, v10, v154
	s_waitcnt lgkmcnt(8)
	v_add_f32_e32 v11, v11, v155
	v_cndmask_b32_e32 v10, v240, v10, vcc
	v_cndmask_b32_e64 v11, v240, v11, s[16:17]
	v_cmp_lt_i32_e32 vcc, 47, v115
	v_cmp_lt_i32_e64 s[16:17], 48, v115
	s_waitcnt lgkmcnt(7)
	v_add_f32_e32 v12, v12, v60
	s_waitcnt lgkmcnt(6)
	v_add_f32_e32 v13, v13, v61
	v_cndmask_b32_e32 v12, v240, v12, vcc
	v_cndmask_b32_e64 v13, v240, v13, s[16:17]
	v_cmp_lt_i32_e32 vcc, 49, v115
	v_cmp_lt_i32_e64 s[16:17], 50, v115
	s_waitcnt lgkmcnt(5)
	v_add_f32_e32 v14, v14, v62
	s_waitcnt lgkmcnt(4)
	v_add_f32_e32 v15, v15, v63
	v_cndmask_b32_e32 v14, v240, v14, vcc
	v_cndmask_b32_e64 v15, v240, v15, s[16:17]
	v_cmp_lt_i32_e32 vcc, 55, v115
	v_cmp_lt_i32_e64 s[16:17], 56, v115
	s_waitcnt lgkmcnt(3)
	v_add_f32_e32 v16, v16, v64
	s_waitcnt lgkmcnt(2)
	v_add_f32_e32 v17, v17, v65
	v_cndmask_b32_e32 v16, v240, v16, vcc
	v_cndmask_b32_e64 v17, v240, v17, s[16:17]
	v_cmp_lt_i32_e32 vcc, 57, v115
	v_cmp_lt_i32_e64 s[16:17], 58, v115
	s_waitcnt lgkmcnt(1)
	v_add_f32_e32 v18, v18, v66
	s_waitcnt lgkmcnt(0)
	v_add_f32_e32 v19, v19, v67
	v_cndmask_b32_e32 v18, v240, v18, vcc
	v_cndmask_b32_e64 v19, v240, v19, s[16:17]

; __device__ __forceinline__ void qkt_rt(f32x16& p0, f32x16& p1, const char* Kb, int r32, int hi, const bf16x8* qr) {
;     p0 = f32x16{}; p1 = f32x16{};
;     const char* kb[4];
; #pragma unroll
;     for (int dd = 0; dd < 4; ++dd) kb[dd] = Kb + KSWZ(r32, (dd * 16 + hi * 8) * 2);
; #pragma unroll
;     for (int d0 = 0; d0 < 8; ++d0) { const char* a = kb[d0 & 3] + (d0 >> 2) * 128;
;         bf16x8 b0 = *reinterpret_cast<const bf16x8*>(a);
;         bf16x8 b1 = *reinterpret_cast<const bf16x8*>(a + 32 * 256);
;         p0 = __builtin_amdgcn_mfma_f32_32x32x16_bf16(b0, qr[d0], p0, 0, 0, 0);
;         p1 = __builtin_amdgcn_mfma_f32_32x32x16_bf16(b1, qr[d0], p1, 0, 0, 0); }
; }
.LBB0_592:
	s_lshl_b32 s10, s88, 15
	s_add_i32 s10, s10, s100
	s_mov_b32 m0, s10
	v_lshl_add_u64 v[52:53], v[168:169], 0, s[82:83]
	global_load_lds_dwordx4 v[52:53], off
	s_add_i32 m0, s10, 0x380
	v_lshl_add_u64 v[54:55], v[170:171], 0, s[82:83]
	global_load_lds_dwordx4 v[52:53], off offset:128
	s_add_i32 m0, s10, 0x4000
	s_nop 0
	global_load_lds_dwordx4 v[54:55], off
	s_add_i32 m0, s10, 0x4380
	s_nop 0
	global_load_lds_dwordx4 v[54:55], off offset:128
	s_add_i32 s10, s16, 0
	s_add_i32 s10, s10, 0x10000
	v_add3_u32 v250, s10, v121, v119
	v_add3_u32 v251, s10, v122, v119
	v_add3_u32 v252, s10, v123, v119
	v_add3_u32 v253, s10, v124, v119
	s_or_b32 s10, s84, 63
	s_cmp_le_i32 s10, s86
	ds_read_b128 v[132:135], v250
	ds_read_b128 v[136:139], v250 offset:8192
	ds_read_b128 v[140:143], v251
	ds_read_b128 v[144:147], v251 offset:8192
	ds_read_b128 v[148:151], v252
	ds_read_b128 v[152:155], v252 offset:8192
	ds_read_b128 v[52:55], v253
	ds_read_b128 v[56:59], v253 offset:8192
	ds_read_b128 v[60:63], v250 offset:128
	ds_read_b128 v[64:67], v250 offset:8320
	ds_read_b128 v[68:71], v251 offset:128
	ds_read_b128 v[72:75], v251 offset:8320
	ds_read_b128 v[36:39], v252 offset:128
	ds_read_b128 v[40:43], v252 offset:8320
	s_waitcnt lgkmcnt(13)
	v_mfma_f32_32x32x16_bf16 v[20:35], v[132:135], v[104:107], 0
	ds_read_b128 v[44:47], v253 offset:128
	s_waitcnt lgkmcnt(13)
	v_mfma_f32_32x32x16_bf16 v[4:19], v[136:139], v[104:107], 0
	ds_read_b128 v[48:51], v253 offset:8320
	s_waitcnt lgkmcnt(13)
	v_mfma_f32_32x32x16_bf16 v[20:35], v[140:143], v[100:103], v[20:35]
	s_waitcnt lgkmcnt(12)
	v_mfma_f32_32x32x16_bf16 v[4:19], v[144:147], v[100:103], v[4:19]
	s_waitcnt lgkmcnt(11)
	v_mfma_f32_32x32x16_bf16 v[20:35], v[148:151], v[96:99], v[20:35]
	s_waitcnt lgkmcnt(10)
	v_mfma_f32_32x32x16_bf16 v[4:19], v[152:155], v[96:99], v[4:19]
	s_waitcnt lgkmcnt(9)
	v_mfma_f32_32x32x16_bf16 v[20:35], v[52:55], v[92:95], v[20:35]
	s_waitcnt lgkmcnt(8)
	v_mfma_f32_32x32x16_bf16 v[4:19], v[56:59], v[92:95], v[4:19]
	s_waitcnt lgkmcnt(7)
	v_mfma_f32_32x32x16_bf16 v[20:35], v[60:63], v[88:91], v[20:35]
	s_waitcnt lgkmcnt(6)
	v_mfma_f32_32x32x16_bf16 v[4:19], v[64:67], v[88:91], v[4:19]
	s_waitcnt lgkmcnt(5)
	v_mfma_f32_32x32x16_bf16 v[20:35], v[68:71], v[84:87], v[20:35]
	s_waitcnt lgkmcnt(4)
	v_mfma_f32_32x32x16_bf16 v[4:19], v[72:75], v[84:87], v[4:19]
	s_waitcnt lgkmcnt(3)
	v_mfma_f32_32x32x16_bf16 v[20:35], v[36:39], v[80:83], v[20:35]
	s_waitcnt lgkmcnt(2)
	v_mfma_f32_32x32x16_bf16 v[4:19], v[40:43], v[80:83], v[4:19]
	s_waitcnt lgkmcnt(1)
	v_mfma_f32_32x32x16_bf16 v[20:35], v[44:47], v[76:79], v[20:35]
	s_waitcnt lgkmcnt(0)
	v_mfma_f32_32x32x16_bf16 v[4:19], v[48:51], v[76:79], v[4:19]
	s_cbranch_scc1 .LBB0_626
; __device__ __forceinline__ void bias_mask_tile(f32x16& p0, f32x16& p1, int dq, const float* bt) {
;     const float NEG = -__builtin_inff();
; #pragma unroll
;     for (int r = 0; r < 16; ++r) {
;         const int c = (r & 3) + 8 * (r >> 2);
;         const int d0 = dq - c, d1 = dq - c - 32;
;         const unsigned i0 = (unsigned)d0 < 255u ? (unsigned)d0 : 255u, i1 = (unsigned)d1 < 255u ? (unsigned)d1 : 255u;
;         const float b0 = bt[i0], b1 = bt[i1];
;         p0[r] = d0 >= 0 ? p0[r] + b0 : NEG;
;         p1[r] = d1 >= 0 ? p1[r] + b1 : NEG;
;     }
; }
	v_or_b32_e32 v36, s85, v211
	v_or_b32_e32 v37, s84, v114
	v_sub_u32_e32 v76, v36, v37
	v_lshl_add_u32 v36, v76, 2, s64
	v_add_u32_e32 v36, 0xffffff14, v36
	ds_read_b32 v132, v36 offset:236
	ds_read_b32 v133, v36 offset:232
	ds_read_b32 v134, v36 offset:228
	ds_read_b32 v135, v36 offset:224
	ds_read_b32 v136, v36 offset:204
	ds_read_b32 v137, v36 offset:200
	ds_read_b32 v138, v36 offset:196
	ds_read_b32 v139, v36 offset:192
	ds_read_b32 v140, v36 offset:172
	ds_read_b32 v141, v36 offset:168
	ds_read_b32 v142, v36 offset:164
	ds_read_b32 v143, v36 offset:160
	ds_read_b32 v144, v36 offset:140
	ds_read_b32 v145, v36 offset:136
	ds_read_b32 v146, v36 offset:132
	v_cmp_lt_i32_e32 vcc, -1, v76
	v_cmp_lt_i32_e64 s[16:17], 0, v76
	s_waitcnt lgkmcnt(14)
	v_add_f32_e32 v20, v20, v132
	ds_read_b32 v147, v36 offset:128
	s_waitcnt lgkmcnt(14)
	v_add_f32_e32 v21, v21, v133
	ds_read_b32 v148, v36 offset:108
	v_cndmask_b32_e32 v20, v240, v20, vcc
	v_cndmask_b32_e64 v21, v240, v21, s[16:17]
	v_cmp_lt_i32_e32 vcc, 1, v76
	v_cmp_lt_i32_e64 s[16:17], 2, v76
	s_waitcnt lgkmcnt(14)
	v_add_f32_e32 v22, v22, v134
	ds_read_b32 v149, v36 offset:104
	s_waitcnt lgkmcnt(14)
	v_add_f32_e32 v23, v23, v135
	ds_read_b32 v150, v36 offset:100
	v_cndmask_b32_e32 v22, v240, v22, vcc
	v_cndmask_b32_e64 v23, v240, v23, s[16:17]
	v_cmp_lt_i32_e32 vcc, 7, v76
	v_cmp_lt_i32_e64 s[16:17], 8, v76
	s_waitcnt lgkmcnt(14)
	v_add_f32_e32 v24, v24, v136
	ds_read_b32 v151, v36 offset:96
	s_waitcnt lgkmcnt(14)
	v_add_f32_e32 v25, v25, v137
	ds_read_b32 v152, v36 offset:76
	v_cndmask_b32_e32 v24, v240, v24, vcc
	v_cndmask_b32_e64 v25, v240, v25, s[16:17]
	v_cmp_lt_i32_e32 vcc, 9, v76
	v_cmp_lt_i32_e64 s[16:17], 10, v76
	s_waitcnt lgkmcnt(14)
	v_add_f32_e32 v26, v26, v138
	ds_read_b32 v153, v36 offset:72
	s_waitcnt lgkmcnt(14)
	v_add_f32_e32 v27, v27, v139
	ds_read_b32 v154, v36 offset:68
	v_cndmask_b32_e32 v26, v240, v26, vcc
	v_cndmask_b32_e64 v27, v240, v27, s[16:17]
	v_cmp_lt_i32_e32 vcc, 15, v76
	v_cmp_lt_i32_e64 s[16:17], 16, v76
	s_waitcnt lgkmcnt(14)
	v_add_f32_e32 v28, v28, v140
	ds_read_b32 v155, v36 offset:64
	s_waitcnt lgkmcnt(14)
	v_add_f32_e32 v29, v29, v141
	ds_read_b32 v60, v36 offset:44
	v_cndmask_b32_e32 v28, v240, v28, vcc
	v_cndmask_b32_e64 v29, v240, v29, s[16:17]
	v_cmp_lt_i32_e32 vcc, 17, v76
	v_cmp_lt_i32_e64 s[16:17], 18, v76
	s_waitcnt lgkmcnt(14)
	v_add_f32_e32 v30, v30, v142
	ds_read_b32 v61, v36 offset:40
	s_waitcnt lgkmcnt(14)
	v_add_f32_e32 v31, v31, v143
	ds_read_b32 v62, v36 offset:36
	v_cndmask_b32_e32 v30, v240, v30, vcc
	v_cndmask_b32_e64 v31, v240, v31, s[16:17]
	v_cmp_lt_i32_e32 vcc, 23, v76
	v_cmp_lt_i32_e64 s[16:17], 24, v76
	s_waitcnt lgkmcnt(14)
	v_add_f32_e32 v32, v32, v144
	ds_read_b32 v63, v36 offset:32
	s_waitcnt lgkmcnt(14)
	v_add_f32_e32 v33, v33, v145
	ds_read_b32 v64, v36 offset:12
	v_cndmask_b32_e32 v32, v240, v32, vcc
	v_cndmask_b32_e64 v33, v240, v33, s[16:17]
	v_cmp_lt_i32_e32 vcc, 25, v76
	v_cmp_lt_i32_e64 s[16:17], 26, v76
	s_waitcnt lgkmcnt(14)
	v_add_f32_e32 v34, v34, v146
	ds_read_b32 v65, v36 offset:8
	s_waitcnt lgkmcnt(14)
	v_add_f32_e32 v35, v35, v147
	ds_read_b32 v66, v36 offset:4
	v_cndmask_b32_e32 v34, v240, v34, vcc
	v_cndmask_b32_e64 v35, v240, v35, s[16:17]
	v_cmp_lt_i32_e32 vcc, 31, v76
	v_cmp_lt_i32_e64 s[16:17], 32, v76
	s_waitcnt lgkmcnt(14)
	v_add_f32_e32 v4, v4, v148
	ds_read_b32 v67, v36 offset:0
	s_waitcnt lgkmcnt(14)
	v_add_f32_e32 v5, v5, v149
	v_cndmask_b32_e32 v4, v240, v4, vcc
	v_cndmask_b32_e64 v5, v240, v5, s[16:17]
	v_cmp_lt_i32_e32 vcc, 33, v76
	v_cmp_lt_i32_e64 s[16:17], 34, v76
	s_waitcnt lgkmcnt(13)
	v_add_f32_e32 v6, v6, v150
	s_waitcnt lgkmcnt(12)
	v_add_f32_e32 v7, v7, v151
	v_cndmask_b32_e32 v6, v240, v6, vcc
	v_cndmask_b32_e64 v7, v240, v7, s[16:17]
	v_cmp_lt_i32_e32 vcc, 39, v76
	v_cmp_lt_i32_e64 s[16:17], 40, v76
	s_waitcnt lgkmcnt(11)
	v_add_f32_e32 v8, v8, v152
	s_waitcnt lgkmcnt(10)
	v_add_f32_e32 v9, v9, v153
	v_cndmask_b32_e32 v8, v240, v8, vcc
	v_cndmask_b32_e64 v9, v240, v9, s[16:17]
	v_cmp_lt_i32_e32 vcc, 41, v76
	v_cmp_lt_i32_e64 s[16:17], 42, v76
	s_waitcnt lgkmcnt(9)
	v_add_f32_e32 v10, v10, v154
	s_waitcnt lgkmcnt(8)
	v_add_f32_e32 v11, v11, v155
	v_cndmask_b32_e32 v10, v240, v10, vcc
	v_cndmask_b32_e64 v11, v240, v11, s[16:17]
	v_cmp_lt_i32_e32 vcc, 47, v76
	v_cmp_lt_i32_e64 s[16:17], 48, v76
	s_waitcnt lgkmcnt(7)
	v_add_f32_e32 v12, v12, v60
	s_waitcnt lgkmcnt(6)
	v_add_f32_e32 v13, v13, v61
	v_cndmask_b32_e32 v12, v240, v12, vcc
	v_cndmask_b32_e64 v13, v240, v13, s[16:17]
	v_cmp_lt_i32_e32 vcc, 49, v76
	v_cmp_lt_i32_e64 s[16:17], 50, v76
	s_waitcnt lgkmcnt(5)
	v_add_f32_e32 v14, v14, v62
	s_waitcnt lgkmcnt(4)
	v_add_f32_e32 v15, v15, v63
	v_cndmask_b32_e32 v14, v240, v14, vcc
	v_cndmask_b32_e64 v15, v240, v15, s[16:17]
	v_cmp_lt_i32_e32 vcc, 55, v76
	v_cmp_lt_i32_e64 s[16:17], 56, v76
	s_waitcnt lgkmcnt(3)
	v_add_f32_e32 v16, v16, v64
	s_waitcnt lgkmcnt(2)
	v_add_f32_e32 v17, v17, v65
	v_cndmask_b32_e32 v16, v240, v16, vcc
	v_cndmask_b32_e64 v17, v240, v17, s[16:17]
	v_cmp_lt_i32_e32 vcc, 57, v76
	v_cmp_lt_i32_e64 s[16:17], 58, v76
	s_waitcnt lgkmcnt(1)
	v_add_f32_e32 v18, v18, v66
	s_waitcnt lgkmcnt(0)
	v_add_f32_e32 v19, v19, v67
	v_cndmask_b32_e32 v18, v240, v18, vcc
	v_cndmask_b32_e64 v19, v240, v19, s[16:17]
